# P + P10: q-gain and k-gain loads issued right after the row-stat loads (latency under the reduction chain)
# speedup vs baseline: 1.0027x; 1.0027x over previous
; #define LAS __attribute__((address_space(3)))
; __device__ __forceinline__ float bflo(unsigned w) { return __uint_as_float(w << 16); }
; __device__ __forceinline__ float bfhi(unsigned w) { return __uint_as_float(w & 0xffff0000u); }
; __device__ __forceinline__ unsigned pk2(float lo, float hi) { return pg8::cvt_pk_bf16(lo, hi); }
;     ...
;     auto norm16 = [&](u32x4& a, u32x4& b, const float* gn, float extra) {
;         float x[16];
; #pragma unroll
;         for (int e = 0; e < 4; ++e) { x[2 * e] = bflo(a[e]); x[2 * e + 1] = bfhi(a[e]); x[8 + 2 * e] = bflo(b[e]); x[9 + 2 * e] = bfhi(b[e]); }
;         float sq = 0.f;
; #pragma unroll
;         for (int e = 0; e < 16; ++e) sq += x[e] * x[e];
;         sq += __shfl_xor(sq, 1); sq += __shfl_xor(sq, 2); sq += __shfl_xor(sq, 4);
;         const float rs = __builtin_amdgcn_rsqf(sq * (1.f / 128.f) + EPS) * extra;
;         const f32x4 g0 = *(const f32x4*)(gn + 8 * kj), g1 = *(const f32x4*)(gn + 8 * kj + 4), g2 = *(const f32x4*)(gn + 64 + 8 * kj), g3 = *(const f32x4*)(gn + 64 + 8 * kj + 4);
;     ...
;         const float rs = pg8::row_rs(ssq, grow0 + 16 * w + fr, fq);
;         float sq = 0.f;
; #pragma unroll
;         for (int nb = 0; nb < 8; ++nb) { acc[nb] = acc[nb] * rs; sq += (acc[nb][0] * acc[nb][0] + acc[nb][1] * acc[nb][1]) + (acc[nb][2] * acc[nb][2] + acc[nb][3] * acc[nb][3]); }
;         sq += __shfl_xor(sq, 16); sq += __shfl_xor(sq, 32);
;         const float rn = __builtin_amdgcn_rsqf(sq * (1.f / 128.f) + EPS) * QSCALE;
; #pragma unroll
;         for (int nb = 0; nb < 8; ++nb) { const f32x4 gv = *(const f32x4*)(qg + 16 * nb + 4 * fq);
;             u32x2 ov; ov.x = pk2(acc[nb][0] * rn * gv[0], acc[nb][1] * rn * gv[1]); ov.y = pk2(acc[nb][2] * rn * gv[2], acc[nb][3] * rn * gv[3]);
;             *(LAS u32x2*)(Qs + (16 * w + fr) * QP + 16 * nb + 4 * fq) = ov; }
.LBB0_57:
	s_waitcnt vmcnt(3)
	v_or_b32_e32 v36, s74, v146
	v_add_u32_e32 v36, v36, v151
	v_ashrrev_i32_e32 v37, 31, v36
	s_waitcnt vmcnt(1)
	v_lshrrev_b32_e32 v78, 4, v161
	v_lshlrev_b64 v[36:37], 7, v[36:37]
	v_lshl_add_u64 v[36:37], s[60:61], 0, v[36:37]
	v_lshlrev_b32_e32 v38, 5, v78
	v_mov_b32_e32 v39, v153
	v_lshl_add_u64 v[40:41], v[36:37], 0, v[38:39]
	global_load_dwordx4 v[36:39], v[40:41], off
	s_nop 0
	global_load_dwordx4 v[40:43], v[40:41], off offset:16
	v_and_b32_e32 v239, 48, v161
	global_load_dwordx4 v[200:203], v239, s[76:77]
	global_load_dwordx4 v[204:207], v239, s[76:77] offset:64
	global_load_dwordx4 v[208:211], v239, s[76:77] offset:128
	global_load_dwordx4 v[212:215], v239, s[76:77] offset:192
	global_load_dwordx4 v[216:219], v239, s[76:77] offset:256
	global_load_dwordx4 v[220:223], v239, s[76:77] offset:320
	global_load_dwordx4 v[224:227], v239, s[76:77] offset:384
	global_load_dwordx4 v[228:231], v239, s[76:77] offset:448
	v_lshlrev_b32_e32 v182, 2, v140
	global_load_dwordx4 v[244:247], v182, s[40:41] offset:16
	global_load_dwordx4 v[240:243], v182, s[40:41]
	global_load_dwordx4 v[248:251], v182, s[40:41] offset:272
	global_load_dwordx4 v[232:235], v182, s[40:41] offset:256
	v_lshlrev_b32_e32 v79, 3, v78
	s_movk_i32 s0, 0x500
	s_mov_b64 s[14:15], 0x40000
	v_bfe_u32 v197, v133, 6, 1
	v_readlane_b32 s16, v255, 15
	v_lshlrev_b32_e32 v156, 2, v78
	v_mov_b32_e32 v236, v181
	v_mov_b32_e32 v237, 0xff800000
	v_mov_b32_e32 v181, 0x3e0293ee
	v_mov_b32_e32 v238, v186
	s_waitcnt vmcnt(13)
	v_mov_b32_e32 v44, v36
	s_waitcnt vmcnt(12)
	v_mov_b32_e32 v45, v40
	v_mov_b32_e32 v40, v37
	v_pk_add_f32 v[36:37], v[44:45], v[40:41]
	v_mov_b32_e32 v40, v38
	v_mov_b32_e32 v41, v42
	v_mov_b32_e32 v42, v39
	v_pk_add_f32 v[38:39], v[40:41], v[42:43]
	s_nop 0
	v_pk_add_f32 v[36:37], v[36:37], v[38:39]
	s_nop 0
	v_add_f32_e32 v36, v36, v37
	ds_bpermute_b32 v37, v193, v36
	s_waitcnt lgkmcnt(0)
	v_add_f32_e32 v36, v36, v37
	ds_bpermute_b32 v37, v194, v36
	s_waitcnt lgkmcnt(0)
	v_add_f32_e32 v36, v36, v37
	v_fmamk_f32 v36, v36, 0x3a000000, v177
	v_rsq_f32_e32 v36, v36
	s_nop 0
	v_pk_mul_f32 v[70:71], v[128:129], v[36:37] op_sel_hi:[1,0]
	v_pk_mul_f32 v[66:67], v[124:125], v[36:37] op_sel_hi:[1,0]
	v_pk_mul_f32 v[68:69], v[130:131], v[36:37] op_sel_hi:[1,0]
	v_pk_mul_f32 v[64:65], v[126:127], v[36:37] op_sel_hi:[1,0]
	v_mov_b32_e32 v40, v71
	v_mov_b32_e32 v41, v67
	v_mov_b32_e32 v38, v70
	v_mov_b32_e32 v39, v66
	v_pk_mul_f32 v[40:41], v[40:41], v[40:41]
	v_mov_b32_e32 v42, v69
	v_mov_b32_e32 v43, v65
	v_pk_fma_f32 v[38:39], v[38:39], v[38:39], v[40:41]
	v_mov_b32_e32 v40, v68
	v_mov_b32_e32 v41, v64
	v_pk_mul_f32 v[42:43], v[42:43], v[42:43]
	v_pk_mul_f32 v[60:61], v[122:123], v[36:37] op_sel_hi:[1,0]
	v_pk_fma_f32 v[40:41], v[40:41], v[40:41], v[42:43]
	v_pk_mul_f32 v[62:63], v[120:121], v[36:37] op_sel_hi:[1,0]
	v_pk_add_f32 v[38:39], v[38:39], v[40:41]
	v_pk_mul_f32 v[40:41], v[60:61], v[60:61]
	v_pk_add_f32 v[38:39], v[38:39], v[38:39] op_sel_hi:[0,1]
	v_pk_mul_f32 v[42:43], v[62:63], v[62:63]
	v_pk_mul_f32 v[58:59], v[116:117], v[36:37] op_sel_hi:[1,0]
	v_pk_mov_b32 v[44:45], v[42:43], v[40:41] op_sel:[1,0]
	v_mov_b32_e32 v43, v41
	v_pk_mul_f32 v[56:57], v[118:119], v[36:37] op_sel_hi:[1,0]
	v_mul_f32_e32 v38, v58, v58
	v_pk_add_f32 v[40:41], v[44:45], v[42:43]
	v_pk_fma_f32 v[42:43], v[58:59], v[58:59], v[38:39] op_sel_hi:[1,1,0]
	v_mul_f32_e32 v38, v56, v56
	v_pk_add_f32 v[40:41], v[40:41], v[40:41] op_sel_hi:[0,1]
	v_pk_fma_f32 v[44:45], v[56:57], v[56:57], v[38:39] op_sel_hi:[1,1,0]
	v_pk_mul_f32 v[52:53], v[114:115], v[36:37] op_sel_hi:[1,0]
	v_pk_mul_f32 v[54:55], v[112:113], v[36:37] op_sel_hi:[1,0]
	v_mul_f32_e32 v40, v52, v52
	v_mul_f32_e32 v42, v54, v54
	v_mul_f32_e32 v44, v55, v55
	v_mul_f32_e32 v38, v53, v53
	v_pk_add_f32 v[42:43], v[42:43], v[44:45]
	v_pk_add_f32 v[38:39], v[40:41], v[38:39]
	v_pk_mul_f32 v[48:49], v[110:111], v[36:37] op_sel_hi:[1,0]
	v_pk_mul_f32 v[50:51], v[108:109], v[36:37] op_sel_hi:[1,0]
	v_pk_add_f32 v[38:39], v[42:43], v[38:39]
	v_pk_mul_f32 v[40:41], v[48:49], v[48:49]
	v_pk_mul_f32 v[42:43], v[50:51], v[50:51]
	v_pk_add_f32 v[38:39], v[38:39], v[38:39] op_sel_hi:[0,1]
	v_pk_mov_b32 v[44:45], v[42:43], v[40:41] op_sel:[1,0]
	v_mov_b32_e32 v43, v41
	v_pk_mul_f32 v[46:47], v[104:105], v[36:37] op_sel_hi:[1,0]
	v_pk_add_f32 v[40:41], v[44:45], v[42:43]
	v_pk_mul_f32 v[44:45], v[106:107], v[36:37] op_sel_hi:[1,0]
	v_mul_f32_e32 v38, v46, v46
	v_pk_fma_f32 v[74:75], v[46:47], v[46:47], v[38:39] op_sel_hi:[1,1,0]
	v_mul_f32_e32 v38, v44, v44
	v_pk_add_f32 v[72:73], v[40:41], v[40:41] op_sel_hi:[0,1]
	v_pk_fma_f32 v[76:77], v[44:45], v[44:45], v[38:39] op_sel_hi:[1,1,0]
	v_pk_mul_f32 v[40:41], v[102:103], v[36:37] op_sel_hi:[1,0]
	v_pk_mul_f32 v[42:43], v[100:101], v[36:37] op_sel_hi:[1,0]
	v_mul_f32_e32 v72, v40, v40
	v_mul_f32_e32 v74, v42, v42
	v_mul_f32_e32 v76, v43, v43
	v_mul_f32_e32 v38, v41, v41
	v_pk_add_f32 v[36:37], v[74:75], v[76:77]
	v_pk_add_f32 v[38:39], v[72:73], v[38:39]
	v_and_b32_e32 v74, 48, v161
	v_pk_add_f32 v[36:37], v[36:37], v[38:39]
	s_nop 0
	v_add_f32_e32 v36, v36, v37
	ds_bpermute_b32 v37, v193, v36
	s_waitcnt lgkmcnt(0)
	v_add_f32_e32 v36, v36, v37
	ds_bpermute_b32 v37, v194, v36
	s_waitcnt lgkmcnt(0)
	v_add_f32_e32 v36, v36, v37
	v_fmamk_f32 v36, v36, 0x3c000000, v177
	v_rsq_f32_e32 v36, v36
	s_nop 0
	v_mul_f32_e32 v72, 0x3e0293ee, v36
	v_mul_lo_u32 v36, v149, s94
	v_add3_u32 v73, 0, v36, v79
	v_mul_f32_e32 v70, v70, v72
	v_mul_f32_e32 v66, v66, v72
	v_mul_f32_e32 v62, v62, v72
	v_mul_f32_e32 v58, v58, v72
	v_mul_f32_e32 v54, v54, v72
	v_mul_f32_e32 v50, v50, v72
	v_mul_f32_e32 v46, v46, v72
	v_mul_f32_e32 v42, v42, v72
	s_waitcnt vmcnt(11)
; #define LAS __attribute__((address_space(3)))
; __device__ __forceinline__ float bflo(unsigned w) { return __uint_as_float(w << 16); }
; __device__ __forceinline__ float bfhi(unsigned w) { return __uint_as_float(w & 0xffff0000u); }
; __device__ __forceinline__ unsigned pk2(float lo, float hi) { return pg8::cvt_pk_bf16(lo, hi); }
;     ...
;     auto norm16 = [&](u32x4& a, u32x4& b, const float* gn, float extra) {
;         float x[16];
; #pragma unroll
;         for (int e = 0; e < 4; ++e) { x[2 * e] = bflo(a[e]); x[2 * e + 1] = bfhi(a[e]); x[8 + 2 * e] = bflo(b[e]); x[9 + 2 * e] = bfhi(b[e]); }
;         float sq = 0.f;
; #pragma unroll
;         for (int e = 0; e < 16; ++e) sq += x[e] * x[e];
;         sq += __shfl_xor(sq, 1); sq += __shfl_xor(sq, 2); sq += __shfl_xor(sq, 4);
;         const float rs = __builtin_amdgcn_rsqf(sq * (1.f / 128.f) + EPS) * extra;
;     ...
;         for (int nb = 0; nb < 8; ++nb) { const f32x4 gv = *(const f32x4*)(qg + 16 * nb + 4 * fq);
;             u32x2 ov; ov.x = pk2(acc[nb][0] * rn * gv[0], acc[nb][1] * rn * gv[1]); ov.y = pk2(acc[nb][2] * rn * gv[2], acc[nb][3] * rn * gv[3]);
;             *(LAS u32x2*)(Qs + (16 * w + fr) * QP + 16 * nb + 4 * fq) = ov; }
	v_mul_f32_e32 v36, v200, v70
	v_mul_f32_e32 v70, v71, v72
	v_mul_f32_e32 v37, v201, v70
	v_cvt_pk_bf16_f32 v36, v36, v37
	v_mul_f32_e32 v37, v68, v72
	v_mul_f32_e32 v37, v202, v37
	v_mul_f32_e32 v38, v69, v72
	v_mul_f32_e32 v38, v203, v38
	v_cvt_pk_bf16_f32 v37, v37, v38
	ds_write_b64 v73, v[36:37]
	s_waitcnt vmcnt(10)
	v_mul_f32_e32 v36, v204, v66
	v_mul_f32_e32 v66, v67, v72
	v_mul_f32_e32 v37, v205, v66
	v_cvt_pk_bf16_f32 v36, v36, v37
	v_mul_f32_e32 v37, v64, v72
	v_mul_f32_e32 v37, v206, v37
	v_mul_f32_e32 v38, v65, v72
	v_mul_f32_e32 v38, v207, v38
	v_cvt_pk_bf16_f32 v37, v37, v38
	ds_write_b64 v73, v[36:37] offset:32
	v_mul_lo_u32 v64, v148, s0
	v_readlane_b32 s0, v255, 14
	s_waitcnt vmcnt(9)
	v_mul_f32_e32 v36, v208, v62
	v_mul_f32_e32 v62, v63, v72
	v_mul_f32_e32 v37, v209, v62
	v_cvt_pk_bf16_f32 v36, v36, v37
	v_mul_f32_e32 v37, v60, v72
	v_mul_f32_e32 v37, v210, v37
	v_mul_f32_e32 v38, v61, v72
	v_mul_f32_e32 v38, v211, v38
	v_cvt_pk_bf16_f32 v37, v37, v38
	ds_write_b64 v73, v[36:37] offset:64
	s_waitcnt vmcnt(8)
	v_mul_f32_e32 v36, v212, v58
	v_mul_f32_e32 v58, v59, v72
	v_mul_f32_e32 v37, v213, v58
	v_cvt_pk_bf16_f32 v36, v36, v37
	v_mul_f32_e32 v37, v56, v72
	v_mul_f32_e32 v37, v214, v37
	v_mul_f32_e32 v38, v57, v72
	v_mul_f32_e32 v38, v215, v38
	v_cvt_pk_bf16_f32 v37, v37, v38
	ds_write_b64 v73, v[36:37] offset:96
	v_lshlrev_b32_e32 v56, 16, v30
	v_and_b32_e32 v57, 0xffff0000, v30
	v_lshlrev_b32_e32 v58, 16, v35
	v_and_b32_e32 v59, 0xffff0000, v35
	s_waitcnt vmcnt(7)
	v_mul_f32_e32 v36, v216, v54
	v_mul_f32_e32 v54, v55, v72
	v_mul_f32_e32 v37, v217, v54
	v_cvt_pk_bf16_f32 v36, v36, v37
	v_mul_f32_e32 v37, v52, v72
	v_mul_f32_e32 v37, v218, v37
	v_mul_f32_e32 v38, v53, v72
	v_mul_f32_e32 v38, v219, v38
	v_cvt_pk_bf16_f32 v37, v37, v38
	ds_write_b64 v73, v[36:37] offset:128
	v_lshlrev_b32_e32 v54, 16, v34
	v_and_b32_e32 v55, 0xffff0000, v34
	v_lshlrev_b32_e32 v52, 16, v29
	v_and_b32_e32 v53, 0xffff0000, v29
	s_waitcnt vmcnt(6)
	v_mul_f32_e32 v36, v220, v50
	v_mul_f32_e32 v50, v51, v72
	v_mul_f32_e32 v37, v221, v50
	v_cvt_pk_bf16_f32 v36, v36, v37
	v_mul_f32_e32 v37, v48, v72
	v_mul_f32_e32 v37, v222, v37
	v_mul_f32_e32 v38, v49, v72
	v_mul_f32_e32 v38, v223, v38
	v_cvt_pk_bf16_f32 v37, v37, v38
	ds_write_b64 v73, v[36:37] offset:160
	v_lshlrev_b32_e32 v50, 16, v33
	v_and_b32_e32 v51, 0xffff0000, v33
	v_lshlrev_b32_e32 v48, 16, v28
	v_and_b32_e32 v49, 0xffff0000, v28
	s_waitcnt vmcnt(5)
	v_mul_f32_e32 v36, v224, v46
	v_mul_f32_e32 v46, v47, v72
	v_mul_f32_e32 v37, v225, v46
	v_cvt_pk_bf16_f32 v36, v36, v37
	v_mul_f32_e32 v37, v44, v72
	v_mul_f32_e32 v37, v226, v37
	v_mul_f32_e32 v38, v45, v72
	v_mul_f32_e32 v38, v227, v38
	v_cvt_pk_bf16_f32 v37, v37, v38
	ds_write_b64 v73, v[36:37] offset:192
	v_and_b32_e32 v47, 0xffff0000, v32
	v_lshlrev_b32_e32 v46, 16, v32
	v_mul_f32_e32 v30, v47, v47
	v_fmac_f32_e32 v30, v46, v46
	v_fmac_f32_e32 v30, v50, v50
	v_fmac_f32_e32 v30, v51, v51
	v_fmac_f32_e32 v30, v54, v54
	v_fmac_f32_e32 v30, v55, v55
	v_fmac_f32_e32 v30, v58, v58
	v_fmac_f32_e32 v30, v59, v59
	v_fmac_f32_e32 v30, v48, v48
	v_fmac_f32_e32 v30, v49, v49
	v_fmac_f32_e32 v30, v52, v52
	v_fmac_f32_e32 v30, v53, v53
	v_fmac_f32_e32 v30, v56, v56
	v_and_b32_e32 v44, 0xffff0000, v31
	v_lshlrev_b32_e32 v45, 16, v31
	v_fmac_f32_e32 v30, v57, v57
	v_pk_mul_f32 v[28:29], v[44:45], v[44:45]
	s_waitcnt vmcnt(4)
	v_mul_f32_e32 v36, v42, v228
	v_add_f32_e32 v29, v29, v30
	v_add_f32_e32 v28, v28, v29
	ds_bpermute_b32 v29, v155, v28
	v_mul_f32_e32 v42, v43, v72
	v_mul_f32_e32 v37, v42, v229
	v_cvt_pk_bf16_f32 v36, v36, v37
	v_mul_f32_e32 v37, v40, v72
	s_waitcnt lgkmcnt(0)
	v_add_f32_e32 v28, v28, v29
	ds_bpermute_b32 v29, v157, v28
	v_mul_f32_e32 v37, v37, v230
	v_mul_f32_e32 v38, v41, v72
	v_mul_f32_e32 v38, v38, v231
	v_cvt_pk_bf16_f32 v37, v37, v38
	s_waitcnt lgkmcnt(0)
	v_add_f32_e32 v28, v28, v29
	ds_bpermute_b32 v29, v192, v28
	v_lshlrev_b32_e32 v40, 2, v140
	v_mov_b32_e32 v41, v153
	ds_write_b64 v73, v[36:37] offset:224
	s_waitcnt lgkmcnt(0)
	v_add_f32_e32 v28, v28, v29
	v_fmamk_f32 v28, v28, 0x3c000000, v177
	s_barrier
; #define LAS __attribute__((address_space(3)))
;     ...
;         a[0] = pk2(x[0] * rs * g0[0], x[1] * rs * g0[1]); a[1] = pk2(x[2] * rs * g0[2], x[3] * rs * g0[3]); a[2] = pk2(x[4] * rs * g1[0], x[5] * rs * g1[1]); a[3] = pk2(x[6] * rs * g1[2], x[7] * rs * g1[3]);
;         b[0] = pk2(x[8] * rs * g2[0], x[9] * rs * g2[1]); b[1] = pk2(x[10] * rs * g2[2], x[11] * rs * g2[3]); b[2] = pk2(x[12] * rs * g3[0], x[13] * rs * g3[1]); b[3] = pk2(x[14] * rs * g3[2], x[15] * rs * g3[3]);
;     };
;     auto load_tile = [&](KVRegs& r, int t) {
;         const bf16* ks = Kp + (size_t)(t * 64 + kr) * ldkv; r.ka = *(const u32x4*)(ks + 8 * kj); r.kb = *(const u32x4*)(ks + 64 + 8 * kj);
;         if (MODE == 0) { const bf16* vs = Vp + (size_t)(tid >> 2) * SEQ + t * 64 + 16 * (tid & 3); r.va = *(const u32x4*)vs; r.vb = *(const u32x4*)(vs + 8); }
;         else { const bf16* vs = Vp + (size_t)(t * 64 + vr) * ldkv; r.va = *(const u32x4*)(vs + 8 * vj); r.vb = *(const u32x4*)(vs + 64 + 8 * vj); } };
;     auto stage = [&](KVRegs& r, int buf) {
;         LAS bf16* Ks = (LAS bf16*)(lds + koff(buf)); LAS bf16* VT = (LAS bf16*)(lds + voff(buf));
;         if (MODE >= 1) norm16(r.ka, r.kb, kg, 1.0f);
;         *(LAS u32x4*)(Ks + kr * QP + 8 * kj) = r.ka; *(LAS u32x4*)(Ks + kr * QP + 64 + 8 * kj) = r.kb;
;         if (MODE == 0) { *(LAS u32x4*)(VT + (tid >> 2) * VPA + 16 * (tid & 3)) = r.va; *(LAS u32x4*)(VT + (tid >> 2) * VPA + 16 * (tid & 3) + 8) = r.vb; }
;         else
; #pragma unroll
;         for (int e = 0; e < 4; ++e) { const int pv = vperm(vr);
;                                       VT[(8 * vj + 2 * e) * VPA + pv] = (bf16)(r.va[e] & 0xffffu); VT[(8 * vj + 2 * e + 1) * VPA + pv] = (bf16)(r.va[e] >> 16);
;                                       VT[(64 + 8 * vj + 2 * e) * VPA + pv] = (bf16)(r.vb[e] & 0xffffu); VT[(64 + 8 * vj + 2 * e + 1) * VPA + pv] = (bf16)(r.vb[e] >> 16); } };
;     ...
;     stage(r0, 0); if (2 < ntiles) load_tile(r0, 2);
;     if (MODE == 0) { stage(r1, 1); if (3 < ntiles) load_tile(r1, 3); }
;     __syncthreads();
;     const int rp = w >> 1, kh = w & 1;
;     bf16x8 qf[2][4];
; #pragma unroll
;     for (int rb = 0; rb < 2; ++rb)
; #pragma unroll
;         for (int ks = 0; ks < 4; ++ks) qf[rb][ks] = *(const LAS bf16x8*)(Qs + (32 * rp + 16 * rb + fr) * QP + 32 * ks + 8 * fq);
;     f32x4 o[2][8];
; #pragma unroll
;     for (int rb = 0; rb < 2; ++rb)
; #pragma unroll
	v_rsq_f32_e32 v60, v28
	v_lshl_add_u64 v[158:159], s[40:41], 0, v[40:41]
	s_mov_b64 s[40:41], -1
	v_mul_f32_e32 v46, v60, v46
	s_waitcnt vmcnt(2)
	v_mul_f32_e32 v32, v240, v46
	v_mul_f32_e32 v46, v60, v47
	v_mul_f32_e32 v33, v241, v46
	v_cvt_pk_bf16_f32 v32, v32, v33
	v_mul_f32_e32 v33, v60, v50
	v_mul_f32_e32 v33, v242, v33
	v_mul_f32_e32 v34, v60, v51
	v_mul_f32_e32 v34, v243, v34
	v_cvt_pk_bf16_f32 v33, v33, v34
	v_mul_f32_e32 v34, v60, v54
	v_mul_f32_e32 v28, v244, v34
	v_mul_f32_e32 v34, v60, v55
	v_mul_f32_e32 v29, v245, v34
	v_cvt_pk_bf16_f32 v34, v28, v29
	v_mul_f32_e32 v28, v60, v58
	v_mul_f32_e32 v29, v60, v59
	v_mul_f32_e32 v28, v246, v28
	v_mul_f32_e32 v29, v247, v29
	v_cvt_pk_bf16_f32 v35, v28, v29
	v_mul_f32_e32 v28, v60, v48
	v_mul_f32_e32 v29, v60, v49
	s_waitcnt vmcnt(0)
	v_mul_f32_e32 v28, v232, v28
	v_mul_f32_e32 v29, v233, v29
	v_cvt_pk_bf16_f32 v28, v28, v29
	v_mul_f32_e32 v29, v60, v52
	v_mul_f32_e32 v30, v60, v53
	v_mul_f32_e32 v29, v234, v29
	v_mul_f32_e32 v30, v235, v30
	v_cvt_pk_bf16_f32 v29, v29, v30
	v_mul_f32_e32 v30, v60, v56
	v_mul_f32_e32 v31, v60, v57
	v_mul_f32_e32 v30, v248, v30
	v_mul_f32_e32 v31, v249, v31
	v_cvt_pk_bf16_f32 v30, v30, v31
	v_mul_f32_e32 v31, v60, v45
	v_mul_f32_e32 v36, v60, v44
	v_mul_f32_e32 v31, v250, v31
	v_mul_f32_e32 v36, v251, v36
	v_cvt_pk_bf16_f32 v31, v31, v36
	v_mul_lo_u32 v36, v138, s94
	v_add_u32_e32 v36, 0, v36
	v_add_u32_e32 v195, v36, v152
	ds_write_b128 v195, v[32:35] offset:36864
	ds_write_b128 v195, v[28:31] offset:36992
	v_lshlrev_b32_e32 v28, 1, v161
	v_lshrrev_b32_e32 v29, 2, v133
	v_and_b32_e32 v28, 24, v28
	v_and_b32_e32 v29, 4, v29
	v_and_b32_e32 v30, 35, v133
	v_or3_b32 v28, v29, v30, v28
	v_lshlrev_b32_e32 v65, 1, v28
	v_add3_u32 v196, s0, v64, v65
	ds_write_b16 v196, v24
	ds_write_b16_d16_hi v196, v24 offset:160
	ds_write_b16 v196, v20 offset:10240
	ds_write_b16_d16_hi v196, v20 offset:10400
	ds_write_b16 v196, v25 offset:320
	ds_write_b16_d16_hi v196, v25 offset:480
	ds_write_b16 v196, v21 offset:10560
	ds_write_b16_d16_hi v196, v21 offset:10720
	ds_write_b16 v196, v26 offset:640
	ds_write_b16_d16_hi v196, v26 offset:800
	ds_write_b16 v196, v22 offset:10880
	ds_write_b16_d16_hi v196, v22 offset:11040
	ds_write_b16 v196, v27 offset:960
	ds_write_b16_d16_hi v196, v27 offset:1120
	ds_write_b16 v196, v23 offset:11200
	ds_write_b16_d16_hi v196, v23 offset:11360
	v_lshlrev_b64 v[20:21], 11, v[138:139]
	v_lshlrev_b32_e32 v152, 1, v140
	v_lshl_add_u64 v[20:21], s[36:37], 0, v[20:21]
	v_lshl_add_u64 v[20:21], v[20:21], 0, v[152:153]
	v_lshl_add_u64 v[22:23], v[20:21], 0, s[14:15]
	s_mov_b32 s14, 0x40000
	v_add_co_u32_e32 v24, vcc, s14, v20
	v_ashrrev_i32_e32 v152, 7, v133
	s_nop 0
	v_addc_co_u32_e32 v25, vcc, 0, v21, vcc
	global_load_dwordx4 v[80:83], v[24:25], off
	global_load_dwordx4 v[88:91], v[22:23], off offset:128
	v_lshl_add_u64 v[22:23], v[136:137], 1, v[134:135]
	v_add_co_u32_e32 v28, vcc, s14, v22
	v_lshl_or_b32 v160, v152, 5, v146
	s_nop 0
	v_addc_co_u32_e32 v29, vcc, 0, v23, vcc
	global_load_dwordx4 v[24:27], v[28:29], off
	s_nop 0
	global_load_dwordx4 v[28:31], v[28:29], off offset:128
	v_mad_u64_u32 v[60:61], s[14:15], v160, s94, v[132:133]
	s_waitcnt lgkmcnt(0)
	s_barrier
	ds_read_b128 v[32:35], v60
	ds_read_b128 v[36:39], v60 offset:64
	ds_read_b128 v[40:43], v60 offset:128
	ds_read_b128 v[44:47], v60 offset:192
	ds_read_b128 v[48:51], v60 offset:4608
	ds_read_b128 v[52:55], v60 offset:4672
	ds_read_b128 v[56:59], v60 offset:4736
	ds_read_b128 v[60:63], v60 offset:4800
	s_mov_b64 s[14:15], 0x60000
	v_lshl_add_u64 v[162:163], v[20:21], 0, s[14:15]
	v_lshl_or_b32 v20, v197, 5, v146
	v_lshl_add_u64 v[164:165], v[22:23], 0, s[14:15]
	s_mov_b64 s[14:15], 0x60080
	v_mul_u32_u24_e32 v21, 0x120, v20
	v_lshlrev_b32_e32 v20, 6, v197
	v_lshl_add_u64 v[166:167], v[22:23], 0, s[14:15]
	v_add3_u32 v22, s0, v20, v147
	v_add3_u32 v23, s16, v20, v147
	v_mov_b32_e32 v20, 0
	v_add3_u32 v198, s16, v64, v65
	v_add_u32_e32 v207, v22, v141
	v_add_u32_e32 v208, v23, v141
	v_add_u32_e32 v209, v132, v21
	v_mov_b32_e32 v21, v20
	v_mov_b32_e32 v22, v20
	v_mov_b32_e32 v23, v20
	v_mov_b32_e32 v64, v20
	v_mov_b32_e32 v65, v20
	v_mov_b32_e32 v66, v20
	v_mov_b32_e32 v67, v20
	v_mov_b32_e32 v68, v20
	v_mov_b32_e32 v69, v20
	v_mov_b32_e32 v70, v20
	v_mov_b32_e32 v71, v20
	v_mov_b32_e32 v72, v20
	v_mov_b32_e32 v73, v20
	v_mov_b32_e32 v74, v20
	v_mov_b32_e32 v75, v20
	v_mov_b32_e32 v76, v20
	v_mov_b32_e32 v77, v20
	v_mov_b32_e32 v78, v20
	v_mov_b32_e32 v79, v20
	v_mov_b32_e32 v84, v20
	v_mov_b32_e32 v85, v20
	v_mov_b32_e32 v86, v20
	v_mov_b32_e32 v87, v20
	v_mov_b32_e32 v92, v20
	v_mov_b32_e32 v93, v20
	v_mov_b32_e32 v94, v20
	v_mov_b32_e32 v95, v20
	v_mov_b32_e32 v96, v20
	v_mov_b32_e32 v97, v20
	v_mov_b32_e32 v98, v20
	v_mov_b32_e32 v99, v20
	v_mov_b32_e32 v100, v20
	v_mov_b32_e32 v101, v20
	v_mov_b32_e32 v102, v20
	v_mov_b32_e32 v103, v20
	v_mov_b32_e32 v104, v20
	v_mov_b32_e32 v105, v20
	v_mov_b32_e32 v106, v20
	v_mov_b32_e32 v107, v20
	v_mov_b32_e32 v108, v20
	v_mov_b32_e32 v109, v20
	v_mov_b32_e32 v110, v20
	v_mov_b32_e32 v111, v20
	v_mov_b32_e32 v112, v20
	v_mov_b32_e32 v113, v20
	v_mov_b32_e32 v114, v20
	v_mov_b32_e32 v115, v20
	v_mov_b32_e32 v116, v20
	v_mov_b32_e32 v117, v20
	v_mov_b32_e32 v118, v20
	v_mov_b32_e32 v119, v20
	v_mov_b32_e32 v120, v20
	v_mov_b32_e32 v121, v20
	v_mov_b32_e32 v122, v20
	v_mov_b32_e32 v123, v20
	v_mov_b32_e32 v124, v20
	v_mov_b32_e32 v125, v20
	s_waitcnt vmcnt(1)
	v_lshrrev_b32_e32 v199, 16, v24
	s_waitcnt vmcnt(0)
	v_lshrrev_b32_e32 v200, 16, v28
	v_lshrrev_b32_e32 v201, 16, v25
	v_lshrrev_b32_e32 v202, 16, v29
	v_lshrrev_b32_e32 v203, 16, v26
	v_lshrrev_b32_e32 v204, 16, v30
	v_lshrrev_b32_e32 v205, 16, v27
	v_lshrrev_b32_e32 v206, 16, v31
	v_mov_b32_e32 v126, v20
	v_mov_b32_e32 v127, v20
	v_mov_b32_e32 v128, v20
	v_mov_b32_e32 v129, v20
	v_mov_b32_e32 v130, v20
	v_mov_b32_e32 v131, v20
	v_mov_b32_e32 v168, v20
	v_mov_b32_e32 v169, v20
	s_branch .LBB0_59
